# gMLP tile epilogue: all u-gate and bias loads issued up front instead of one load + vmcnt(0) per 4 outputs
# baseline (speedup 1.0000x reference)
.LBB0_988:
	s_movk_i32 s4, 0x100
	v_cmp_gt_u32_e32 vcc, s4, v212
	s_waitcnt vmcnt(0)
	s_barrier
	s_and_saveexec_b64 s[4:5], vcc
	s_xor_b64 s[4:5], exec, s[4:5]
	s_cbranch_execz .LBB0_990
	v_or_b32_e32 v1, s16, v212
	s_lshl_b32 s17, s15, 7
	v_lshrrev_b32_e32 v1, 6, v1
	v_lshl_or_b32 v130, v1, 11, s17
	v_lshl_add_u32 v1, v1, 8, s17
	s_lshl_b32 s11, s12, 7
	v_add_u32_e32 v1, 0x8000, v1
	v_cndmask_b32_e64 v1, v130, v1, s[2:3]
	v_or_b32_e32 v130, s11, v219
	v_readlane_b32 s2, v254, 62
	v_ashrrev_i32_e32 v131, 31, v130
	v_readlane_b32 s3, v254, 63
	s_lshl_b32 s12, s14, 6
	v_or_b32_e32 v210, v1, v219
	v_lshl_add_u64 v[130:131], v[130:131], 2, s[2:3]
	s_ashr_i32 s13, s12, 31
	global_load_dword v132, v[130:131], off
	global_load_dword v230, v[130:131], off offset:64
	global_load_dword v231, v[130:131], off offset:128
	global_load_dword v232, v[130:131], off offset:192
	global_load_dword v233, v[130:131], off offset:256
	global_load_dword v234, v[130:131], off offset:320
	global_load_dword v235, v[130:131], off offset:384
	global_load_dword v236, v[130:131], off offset:448
	v_lshlrev_b64 v[130:131], 9, v[210:211]
	s_lshl_b64 s[14:15], s[12:13], 1
	v_lshl_add_u64 v[130:131], s[96:97], 0, v[130:131]
	v_lshl_add_u64 v[134:135], v[130:131], 0, s[14:15]
	v_lshlrev_b32_e32 v130, 3, v221
	v_mov_b32_e32 v131, v211
	v_lshl_add_u64 v[134:135], v[134:135], 0, v[130:131]
	global_load_dwordx2 v[144:145], v[134:135], off
	global_load_dwordx2 v[146:147], v[134:135], off offset:32
	global_load_dwordx2 v[148:149], v[134:135], off offset:64
	global_load_dwordx2 v[150:151], v[134:135], off offset:96
	v_add_co_u32_e32 v140, vcc, 0x2000, v134
	v_addc_co_u32_e32 v141, vcc, 0, v135, vcc
	global_load_dwordx2 v[152:153], v[140:141], off
	global_load_dwordx2 v[154:155], v[140:141], off offset:32
	global_load_dwordx2 v[156:157], v[140:141], off offset:64
	global_load_dwordx2 v[158:159], v[140:141], off offset:96
	v_add_co_u32_e32 v140, vcc, 0x4000, v134
	v_addc_co_u32_e32 v141, vcc, 0, v135, vcc
	global_load_dwordx2 v[160:161], v[140:141], off
	global_load_dwordx2 v[162:163], v[140:141], off offset:32
	global_load_dwordx2 v[164:165], v[140:141], off offset:64
	global_load_dwordx2 v[166:167], v[140:141], off offset:96
	v_add_co_u32_e32 v140, vcc, 0x6000, v134
	v_addc_co_u32_e32 v141, vcc, 0, v135, vcc
	global_load_dwordx2 v[168:169], v[140:141], off
	global_load_dwordx2 v[170:171], v[140:141], off offset:32
	global_load_dwordx2 v[172:173], v[140:141], off offset:64
	global_load_dwordx2 v[174:175], v[140:141], off offset:96
	v_add_co_u32_e32 v140, vcc, 0x8000, v134
	v_addc_co_u32_e32 v141, vcc, 0, v135, vcc
	global_load_dwordx2 v[176:177], v[140:141], off
	global_load_dwordx2 v[178:179], v[140:141], off offset:32
	global_load_dwordx2 v[180:181], v[140:141], off offset:64
	global_load_dwordx2 v[182:183], v[140:141], off offset:96
	v_add_co_u32_e32 v140, vcc, 0xa000, v134
	v_addc_co_u32_e32 v141, vcc, 0, v135, vcc
	global_load_dwordx2 v[184:185], v[140:141], off
	global_load_dwordx2 v[186:187], v[140:141], off offset:32
	global_load_dwordx2 v[188:189], v[140:141], off offset:64
	global_load_dwordx2 v[190:191], v[140:141], off offset:96
	v_add_co_u32_e32 v140, vcc, 0xc000, v134
	v_addc_co_u32_e32 v141, vcc, 0, v135, vcc
	global_load_dwordx2 v[192:193], v[140:141], off
	global_load_dwordx2 v[194:195], v[140:141], off offset:32
	global_load_dwordx2 v[196:197], v[140:141], off offset:64
	global_load_dwordx2 v[198:199], v[140:141], off offset:96
	v_add_co_u32_e32 v140, vcc, 0xe000, v134
	v_addc_co_u32_e32 v141, vcc, 0, v135, vcc
	global_load_dwordx2 v[200:201], v[140:141], off
	global_load_dwordx2 v[202:203], v[140:141], off offset:32
	global_load_dwordx2 v[204:205], v[140:141], off offset:64
	global_load_dwordx2 v[206:207], v[140:141], off offset:96
	s_waitcnt vmcnt(0)
	v_mov_b32_e32 v136, v144
	v_mov_b32_e32 v137, v145
	s_add_u32 s12, s64, s14
	s_addc_u32 s13, s65, s15
	v_pk_add_f32 v[126:127], v[126:127], v[132:133] op_sel_hi:[1,0]
	v_pk_add_f32 v[128:129], v[128:129], v[132:133] op_sel_hi:[1,0]
	v_pk_add_f32 v[122:123], v[122:123], v[132:133] op_sel_hi:[1,0]
	v_pk_add_f32 v[124:125], v[124:125], v[132:133] op_sel_hi:[1,0]
	v_pk_add_f32 v[118:119], v[118:119], v[132:133] op_sel_hi:[1,0]
	v_pk_add_f32 v[120:121], v[120:121], v[132:133] op_sel_hi:[1,0]
	v_pk_add_f32 v[114:115], v[114:115], v[132:133] op_sel_hi:[1,0]
	v_pk_add_f32 v[116:117], v[116:117], v[132:133] op_sel_hi:[1,0]
	v_cvt_f32_f16_e32 v138, v136
	v_cvt_f32_f16_sdwa v139, v136 dst_sel:DWORD dst_unused:UNUSED_PAD src0_sel:WORD_1
	v_cvt_f32_f16_e32 v136, v137
	v_cvt_f32_f16_sdwa v137, v137 dst_sel:DWORD dst_unused:UNUSED_PAD src0_sel:WORD_1
	v_pk_mul_f32 v[126:127], v[126:127], v[138:139]
	s_nop 0
	v_cvt_pk_f16_f32 v126, v126, v127
	v_pk_mul_f32 v[128:129], v[128:129], v[136:137]
	s_nop 0
	v_cvt_pk_f16_f32 v127, v128, v129
	v_lshlrev_b64 v[128:129], 11, v[210:211]
	v_lshl_add_u64 v[128:129], s[12:13], 0, v[128:129]
	v_lshl_add_u64 v[128:129], v[128:129], 0, v[130:131]
	global_store_dwordx2 v[128:129], v[126:127], off
	v_mov_b32_e32 v126, v146
	v_mov_b32_e32 v127, v147
	v_cvt_f32_f16_e32 v136, v126
	v_cvt_f32_f16_sdwa v137, v126 dst_sel:DWORD dst_unused:UNUSED_PAD src0_sel:WORD_1
	v_cvt_f32_f16_e32 v126, v127
	v_cvt_f32_f16_sdwa v127, v127 dst_sel:DWORD dst_unused:UNUSED_PAD src0_sel:WORD_1
	v_pk_mul_f32 v[122:123], v[122:123], v[136:137]
	s_nop 0
	v_cvt_pk_f16_f32 v122, v122, v123
	v_pk_mul_f32 v[124:125], v[124:125], v[126:127]
	s_nop 0
	v_cvt_pk_f16_f32 v123, v124, v125
	global_store_dwordx2 v[128:129], v[122:123], off offset:32
	v_mov_b32_e32 v122, v148
	v_mov_b32_e32 v123, v149
	v_cvt_f32_f16_e32 v124, v122
	v_cvt_f32_f16_sdwa v125, v122 dst_sel:DWORD dst_unused:UNUSED_PAD src0_sel:WORD_1
	v_cvt_f32_f16_e32 v122, v123
	v_cvt_f32_f16_sdwa v123, v123 dst_sel:DWORD dst_unused:UNUSED_PAD src0_sel:WORD_1
	v_pk_mul_f32 v[118:119], v[118:119], v[124:125]
	s_nop 0
	v_cvt_pk_f16_f32 v118, v118, v119
	v_pk_mul_f32 v[120:121], v[120:121], v[122:123]
	s_nop 0
	v_cvt_pk_f16_f32 v119, v120, v121
	global_store_dwordx2 v[128:129], v[118:119], off offset:64
	v_mov_b32_e32 v118, v150
	v_mov_b32_e32 v119, v151
	v_cvt_f32_f16_e32 v120, v118
	v_cvt_f32_f16_sdwa v121, v118 dst_sel:DWORD dst_unused:UNUSED_PAD src0_sel:WORD_1
	v_cvt_f32_f16_e32 v118, v119
	v_cvt_f32_f16_sdwa v119, v119 dst_sel:DWORD dst_unused:UNUSED_PAD src0_sel:WORD_1
	v_pk_mul_f32 v[114:115], v[114:115], v[120:121]
	s_nop 0
	v_cvt_pk_f16_f32 v114, v114, v115
	v_pk_mul_f32 v[116:117], v[116:117], v[118:119]
	s_nop 0
	v_cvt_pk_f16_f32 v115, v116, v117
	v_or_b32_e32 v116, 16, v219
	v_or_b32_e32 v210, v1, v116
	global_store_dwordx2 v[128:129], v[114:115], off offset:96
	v_or_b32_e32 v114, s11, v116
	v_lshlrev_b64 v[116:117], 9, v[210:211]
	v_lshl_add_u64 v[116:117], s[96:97], 0, v[116:117]
	v_ashrrev_i32_e32 v115, 31, v114
	v_lshl_add_u64 v[116:117], v[116:117], 0, s[14:15]
	v_lshl_add_u64 v[114:115], v[114:115], 2, s[2:3]
	v_lshl_add_u64 v[116:117], v[116:117], 0, v[130:131]
	v_mov_b32_e32 v114, v230
	s_nop 0
	v_mov_b32_e32 v118, v152
	v_mov_b32_e32 v119, v153
	v_pk_add_f32 v[110:111], v[110:111], v[114:115] op_sel_hi:[1,0]
	v_pk_add_f32 v[112:113], v[112:113], v[114:115] op_sel_hi:[1,0]
	v_cvt_f32_f16_e32 v120, v118
	v_cvt_f32_f16_sdwa v121, v118 dst_sel:DWORD dst_unused:UNUSED_PAD src0_sel:WORD_1
	v_cvt_f32_f16_e32 v118, v119
	v_cvt_f32_f16_sdwa v119, v119 dst_sel:DWORD dst_unused:UNUSED_PAD src0_sel:WORD_1
	v_pk_add_f32 v[106:107], v[106:107], v[114:115] op_sel_hi:[1,0]
	v_pk_mul_f32 v[110:111], v[110:111], v[120:121]
	v_pk_add_f32 v[108:109], v[108:109], v[114:115] op_sel_hi:[1,0]
	v_pk_mul_f32 v[112:113], v[112:113], v[118:119]
	v_cvt_pk_f16_f32 v110, v110, v111
	v_cvt_pk_f16_f32 v111, v112, v113
	v_lshlrev_b64 v[112:113], 11, v[210:211]
	v_lshl_add_u64 v[112:113], s[12:13], 0, v[112:113]
	v_lshl_add_u64 v[112:113], v[112:113], 0, v[130:131]
	global_store_dwordx2 v[112:113], v[110:111], off
	v_mov_b32_e32 v110, v154
	v_mov_b32_e32 v111, v155
	v_pk_add_f32 v[102:103], v[102:103], v[114:115] op_sel_hi:[1,0]
	v_pk_add_f32 v[104:105], v[104:105], v[114:115] op_sel_hi:[1,0]
	v_pk_add_f32 v[98:99], v[98:99], v[114:115] op_sel_hi:[1,0]
	v_pk_add_f32 v[100:101], v[100:101], v[114:115] op_sel_hi:[1,0]
	v_cvt_f32_f16_e32 v118, v110
	v_cvt_f32_f16_sdwa v119, v110 dst_sel:DWORD dst_unused:UNUSED_PAD src0_sel:WORD_1
	v_cvt_f32_f16_e32 v110, v111
	v_cvt_f32_f16_sdwa v111, v111 dst_sel:DWORD dst_unused:UNUSED_PAD src0_sel:WORD_1
	v_pk_mul_f32 v[106:107], v[106:107], v[118:119]
	s_nop 0
	v_cvt_pk_f16_f32 v106, v106, v107
	v_pk_mul_f32 v[108:109], v[108:109], v[110:111]
	s_nop 0
	v_cvt_pk_f16_f32 v107, v108, v109
	global_store_dwordx2 v[112:113], v[106:107], off offset:32
	v_mov_b32_e32 v106, v156
	v_mov_b32_e32 v107, v157
	v_cvt_f32_f16_e32 v108, v106
	v_cvt_f32_f16_sdwa v109, v106 dst_sel:DWORD dst_unused:UNUSED_PAD src0_sel:WORD_1
	v_cvt_f32_f16_e32 v106, v107
	v_cvt_f32_f16_sdwa v107, v107 dst_sel:DWORD dst_unused:UNUSED_PAD src0_sel:WORD_1
	v_pk_mul_f32 v[102:103], v[102:103], v[108:109]
	s_nop 0
	v_cvt_pk_f16_f32 v102, v102, v103
	v_pk_mul_f32 v[104:105], v[104:105], v[106:107]
	s_nop 0
	v_cvt_pk_f16_f32 v103, v104, v105
	global_store_dwordx2 v[112:113], v[102:103], off offset:64
	v_mov_b32_e32 v102, v158
	v_mov_b32_e32 v103, v159
	v_cvt_f32_f16_e32 v104, v102
	v_cvt_f32_f16_sdwa v105, v102 dst_sel:DWORD dst_unused:UNUSED_PAD src0_sel:WORD_1
	v_cvt_f32_f16_e32 v102, v103
	v_cvt_f32_f16_sdwa v103, v103 dst_sel:DWORD dst_unused:UNUSED_PAD src0_sel:WORD_1
	v_pk_mul_f32 v[98:99], v[98:99], v[104:105]
	s_nop 0
	v_cvt_pk_f16_f32 v98, v98, v99
	v_pk_mul_f32 v[100:101], v[100:101], v[102:103]
	s_nop 0
	v_cvt_pk_f16_f32 v99, v100, v101
	v_or_b32_e32 v100, 32, v219
	v_or_b32_e32 v210, v1, v100
	global_store_dwordx2 v[112:113], v[98:99], off offset:96
	v_or_b32_e32 v98, s11, v100
	v_lshlrev_b64 v[100:101], 9, v[210:211]
	v_lshl_add_u64 v[100:101], s[96:97], 0, v[100:101]
	v_ashrrev_i32_e32 v99, 31, v98
	v_lshl_add_u64 v[100:101], v[100:101], 0, s[14:15]
	v_lshl_add_u64 v[98:99], v[98:99], 2, s[2:3]
	v_lshl_add_u64 v[100:101], v[100:101], 0, v[130:131]
	v_mov_b32_e32 v98, v231
	s_nop 0
	v_mov_b32_e32 v102, v160
	v_mov_b32_e32 v103, v161
	v_pk_add_f32 v[94:95], v[94:95], v[98:99] op_sel_hi:[1,0]
	v_pk_add_f32 v[96:97], v[96:97], v[98:99] op_sel_hi:[1,0]
	v_cvt_f32_f16_e32 v104, v102
	v_cvt_f32_f16_sdwa v105, v102 dst_sel:DWORD dst_unused:UNUSED_PAD src0_sel:WORD_1
	v_cvt_f32_f16_e32 v102, v103
	v_cvt_f32_f16_sdwa v103, v103 dst_sel:DWORD dst_unused:UNUSED_PAD src0_sel:WORD_1
	v_pk_add_f32 v[90:91], v[90:91], v[98:99] op_sel_hi:[1,0]
	v_pk_mul_f32 v[94:95], v[94:95], v[104:105]
	v_pk_add_f32 v[92:93], v[92:93], v[98:99] op_sel_hi:[1,0]
	v_pk_mul_f32 v[96:97], v[96:97], v[102:103]
	v_cvt_pk_f16_f32 v94, v94, v95
	v_cvt_pk_f16_f32 v95, v96, v97
	v_lshlrev_b64 v[96:97], 11, v[210:211]
	v_lshl_add_u64 v[96:97], s[12:13], 0, v[96:97]
	v_lshl_add_u64 v[96:97], v[96:97], 0, v[130:131]
	global_store_dwordx2 v[96:97], v[94:95], off
	v_mov_b32_e32 v94, v162
	v_mov_b32_e32 v95, v163
	v_pk_add_f32 v[86:87], v[86:87], v[98:99] op_sel_hi:[1,0]
	v_pk_add_f32 v[88:89], v[88:89], v[98:99] op_sel_hi:[1,0]
	v_pk_add_f32 v[82:83], v[82:83], v[98:99] op_sel_hi:[1,0]
	v_pk_add_f32 v[84:85], v[84:85], v[98:99] op_sel_hi:[1,0]
	v_cvt_f32_f16_e32 v102, v94
	v_cvt_f32_f16_sdwa v103, v94 dst_sel:DWORD dst_unused:UNUSED_PAD src0_sel:WORD_1
	v_cvt_f32_f16_e32 v94, v95
	v_cvt_f32_f16_sdwa v95, v95 dst_sel:DWORD dst_unused:UNUSED_PAD src0_sel:WORD_1
	v_pk_mul_f32 v[90:91], v[90:91], v[102:103]
	s_nop 0
	v_cvt_pk_f16_f32 v90, v90, v91
	v_pk_mul_f32 v[92:93], v[92:93], v[94:95]
	s_nop 0
	v_cvt_pk_f16_f32 v91, v92, v93
	global_store_dwordx2 v[96:97], v[90:91], off offset:32
	v_mov_b32_e32 v90, v164
	v_mov_b32_e32 v91, v165
	v_cvt_f32_f16_e32 v92, v90
	v_cvt_f32_f16_sdwa v93, v90 dst_sel:DWORD dst_unused:UNUSED_PAD src0_sel:WORD_1
	v_cvt_f32_f16_e32 v90, v91
	v_cvt_f32_f16_sdwa v91, v91 dst_sel:DWORD dst_unused:UNUSED_PAD src0_sel:WORD_1
	v_pk_mul_f32 v[86:87], v[86:87], v[92:93]
	s_nop 0
	v_cvt_pk_f16_f32 v86, v86, v87
	v_pk_mul_f32 v[88:89], v[88:89], v[90:91]
	s_nop 0
	v_cvt_pk_f16_f32 v87, v88, v89
	global_store_dwordx2 v[96:97], v[86:87], off offset:64
	v_mov_b32_e32 v86, v166
	v_mov_b32_e32 v87, v167
	v_cvt_f32_f16_e32 v88, v86
	v_cvt_f32_f16_sdwa v89, v86 dst_sel:DWORD dst_unused:UNUSED_PAD src0_sel:WORD_1
	v_cvt_f32_f16_e32 v86, v87
	v_cvt_f32_f16_sdwa v87, v87 dst_sel:DWORD dst_unused:UNUSED_PAD src0_sel:WORD_1
	v_pk_mul_f32 v[82:83], v[82:83], v[88:89]
	s_nop 0
	v_cvt_pk_f16_f32 v82, v82, v83
	v_pk_mul_f32 v[84:85], v[84:85], v[86:87]
	s_nop 0
	v_cvt_pk_f16_f32 v83, v84, v85
	v_or_b32_e32 v84, 48, v219
	v_or_b32_e32 v210, v1, v84
	global_store_dwordx2 v[96:97], v[82:83], off offset:96
	v_or_b32_e32 v82, s11, v84
	v_lshlrev_b64 v[84:85], 9, v[210:211]
	v_lshl_add_u64 v[84:85], s[96:97], 0, v[84:85]
	v_ashrrev_i32_e32 v83, 31, v82
	v_lshl_add_u64 v[84:85], v[84:85], 0, s[14:15]
	v_lshl_add_u64 v[82:83], v[82:83], 2, s[2:3]
	v_lshl_add_u64 v[84:85], v[84:85], 0, v[130:131]
	v_mov_b32_e32 v82, v232
	s_nop 0
	v_mov_b32_e32 v86, v168
	v_mov_b32_e32 v87, v169
	v_pk_add_f32 v[78:79], v[78:79], v[82:83] op_sel_hi:[1,0]
	v_pk_add_f32 v[80:81], v[80:81], v[82:83] op_sel_hi:[1,0]
	v_cvt_f32_f16_e32 v88, v86
	v_cvt_f32_f16_sdwa v89, v86 dst_sel:DWORD dst_unused:UNUSED_PAD src0_sel:WORD_1
	v_cvt_f32_f16_e32 v86, v87
	v_cvt_f32_f16_sdwa v87, v87 dst_sel:DWORD dst_unused:UNUSED_PAD src0_sel:WORD_1
	v_pk_add_f32 v[74:75], v[74:75], v[82:83] op_sel_hi:[1,0]
	v_pk_mul_f32 v[78:79], v[78:79], v[88:89]
	v_pk_add_f32 v[76:77], v[76:77], v[82:83] op_sel_hi:[1,0]
	v_pk_mul_f32 v[80:81], v[80:81], v[86:87]
	v_cvt_pk_f16_f32 v78, v78, v79
	v_cvt_pk_f16_f32 v79, v80, v81
	v_lshlrev_b64 v[80:81], 11, v[210:211]
	v_lshl_add_u64 v[80:81], s[12:13], 0, v[80:81]
	v_lshl_add_u64 v[80:81], v[80:81], 0, v[130:131]
	global_store_dwordx2 v[80:81], v[78:79], off
	v_mov_b32_e32 v78, v170
	v_mov_b32_e32 v79, v171
	v_pk_add_f32 v[70:71], v[70:71], v[82:83] op_sel_hi:[1,0]
	v_pk_add_f32 v[72:73], v[72:73], v[82:83] op_sel_hi:[1,0]
	v_pk_add_f32 v[66:67], v[66:67], v[82:83] op_sel_hi:[1,0]
	v_pk_add_f32 v[68:69], v[68:69], v[82:83] op_sel_hi:[1,0]
	v_cvt_f32_f16_e32 v86, v78
	v_cvt_f32_f16_sdwa v87, v78 dst_sel:DWORD dst_unused:UNUSED_PAD src0_sel:WORD_1
	v_cvt_f32_f16_e32 v78, v79
	v_cvt_f32_f16_sdwa v79, v79 dst_sel:DWORD dst_unused:UNUSED_PAD src0_sel:WORD_1
	v_pk_mul_f32 v[74:75], v[74:75], v[86:87]
	s_nop 0
	v_cvt_pk_f16_f32 v74, v74, v75
	v_pk_mul_f32 v[76:77], v[76:77], v[78:79]
	s_nop 0
	v_cvt_pk_f16_f32 v75, v76, v77
	global_store_dwordx2 v[80:81], v[74:75], off offset:32
	v_mov_b32_e32 v74, v172
	v_mov_b32_e32 v75, v173
	v_cvt_f32_f16_e32 v76, v74
	v_cvt_f32_f16_sdwa v77, v74 dst_sel:DWORD dst_unused:UNUSED_PAD src0_sel:WORD_1
	v_cvt_f32_f16_e32 v74, v75
	v_cvt_f32_f16_sdwa v75, v75 dst_sel:DWORD dst_unused:UNUSED_PAD src0_sel:WORD_1
	v_pk_mul_f32 v[70:71], v[70:71], v[76:77]
	s_nop 0
	v_cvt_pk_f16_f32 v70, v70, v71
	v_pk_mul_f32 v[72:73], v[72:73], v[74:75]
	s_nop 0
	v_cvt_pk_f16_f32 v71, v72, v73
	global_store_dwordx2 v[80:81], v[70:71], off offset:64
	v_mov_b32_e32 v70, v174
	v_mov_b32_e32 v71, v175
	v_cvt_f32_f16_e32 v72, v70
	v_cvt_f32_f16_sdwa v73, v70 dst_sel:DWORD dst_unused:UNUSED_PAD src0_sel:WORD_1
	v_cvt_f32_f16_e32 v70, v71
	v_cvt_f32_f16_sdwa v71, v71 dst_sel:DWORD dst_unused:UNUSED_PAD src0_sel:WORD_1
	v_pk_mul_f32 v[66:67], v[66:67], v[72:73]
	s_nop 0
	v_cvt_pk_f16_f32 v66, v66, v67
	v_pk_mul_f32 v[68:69], v[68:69], v[70:71]
	s_nop 0
	v_cvt_pk_f16_f32 v67, v68, v69
	v_or_b32_e32 v68, 64, v219
	v_or_b32_e32 v210, v1, v68
	global_store_dwordx2 v[80:81], v[66:67], off offset:96
	v_or_b32_e32 v66, s11, v68
	v_lshlrev_b64 v[68:69], 9, v[210:211]
	v_lshl_add_u64 v[68:69], s[96:97], 0, v[68:69]
	v_ashrrev_i32_e32 v67, 31, v66
	v_lshl_add_u64 v[68:69], v[68:69], 0, s[14:15]
	v_lshl_add_u64 v[66:67], v[66:67], 2, s[2:3]
	v_lshl_add_u64 v[68:69], v[68:69], 0, v[130:131]
	v_mov_b32_e32 v66, v233
	s_nop 0
	v_mov_b32_e32 v70, v176
	v_mov_b32_e32 v71, v177
	v_pk_add_f32 v[62:63], v[62:63], v[66:67] op_sel_hi:[1,0]
	v_pk_add_f32 v[64:65], v[64:65], v[66:67] op_sel_hi:[1,0]
	v_cvt_f32_f16_e32 v72, v70
	v_cvt_f32_f16_sdwa v73, v70 dst_sel:DWORD dst_unused:UNUSED_PAD src0_sel:WORD_1
	v_cvt_f32_f16_e32 v70, v71
	v_cvt_f32_f16_sdwa v71, v71 dst_sel:DWORD dst_unused:UNUSED_PAD src0_sel:WORD_1
	v_pk_add_f32 v[58:59], v[58:59], v[66:67] op_sel_hi:[1,0]
	v_pk_mul_f32 v[62:63], v[62:63], v[72:73]
	v_pk_add_f32 v[60:61], v[60:61], v[66:67] op_sel_hi:[1,0]
	v_pk_mul_f32 v[64:65], v[64:65], v[70:71]
	v_cvt_pk_f16_f32 v62, v62, v63
	v_cvt_pk_f16_f32 v63, v64, v65
	v_lshlrev_b64 v[64:65], 11, v[210:211]
	v_lshl_add_u64 v[64:65], s[12:13], 0, v[64:65]
	v_lshl_add_u64 v[64:65], v[64:65], 0, v[130:131]
	global_store_dwordx2 v[64:65], v[62:63], off
	v_mov_b32_e32 v62, v178
	v_mov_b32_e32 v63, v179
	v_pk_add_f32 v[54:55], v[54:55], v[66:67] op_sel_hi:[1,0]
	v_pk_add_f32 v[56:57], v[56:57], v[66:67] op_sel_hi:[1,0]
	v_pk_add_f32 v[50:51], v[50:51], v[66:67] op_sel_hi:[1,0]
	v_pk_add_f32 v[52:53], v[52:53], v[66:67] op_sel_hi:[1,0]
	v_cvt_f32_f16_e32 v70, v62
	v_cvt_f32_f16_sdwa v71, v62 dst_sel:DWORD dst_unused:UNUSED_PAD src0_sel:WORD_1
	v_cvt_f32_f16_e32 v62, v63
	v_cvt_f32_f16_sdwa v63, v63 dst_sel:DWORD dst_unused:UNUSED_PAD src0_sel:WORD_1
	v_pk_mul_f32 v[58:59], v[58:59], v[70:71]
	s_nop 0
	v_cvt_pk_f16_f32 v58, v58, v59
	v_pk_mul_f32 v[60:61], v[60:61], v[62:63]
	s_nop 0
	v_cvt_pk_f16_f32 v59, v60, v61
	global_store_dwordx2 v[64:65], v[58:59], off offset:32
	v_mov_b32_e32 v58, v180
	v_mov_b32_e32 v59, v181
	v_cvt_f32_f16_e32 v60, v58
	v_cvt_f32_f16_sdwa v61, v58 dst_sel:DWORD dst_unused:UNUSED_PAD src0_sel:WORD_1
	v_cvt_f32_f16_e32 v58, v59
	v_cvt_f32_f16_sdwa v59, v59 dst_sel:DWORD dst_unused:UNUSED_PAD src0_sel:WORD_1
	v_pk_mul_f32 v[54:55], v[54:55], v[60:61]
	s_nop 0
	v_cvt_pk_f16_f32 v54, v54, v55
	v_pk_mul_f32 v[56:57], v[56:57], v[58:59]
	s_nop 0
	v_cvt_pk_f16_f32 v55, v56, v57
	global_store_dwordx2 v[64:65], v[54:55], off offset:64
	v_mov_b32_e32 v54, v182
	v_mov_b32_e32 v55, v183
	v_cvt_f32_f16_e32 v56, v54
	v_cvt_f32_f16_sdwa v57, v54 dst_sel:DWORD dst_unused:UNUSED_PAD src0_sel:WORD_1
	v_cvt_f32_f16_e32 v54, v55
	v_cvt_f32_f16_sdwa v55, v55 dst_sel:DWORD dst_unused:UNUSED_PAD src0_sel:WORD_1
	v_pk_mul_f32 v[50:51], v[50:51], v[56:57]
	s_nop 0
	v_cvt_pk_f16_f32 v50, v50, v51
	v_pk_mul_f32 v[52:53], v[52:53], v[54:55]
	s_nop 0
	v_cvt_pk_f16_f32 v51, v52, v53
	v_or_b32_e32 v52, 0x50, v219
	v_or_b32_e32 v210, v1, v52
	global_store_dwordx2 v[64:65], v[50:51], off offset:96
	v_or_b32_e32 v50, s11, v52
	v_lshlrev_b64 v[52:53], 9, v[210:211]
	v_lshl_add_u64 v[52:53], s[96:97], 0, v[52:53]
	v_ashrrev_i32_e32 v51, 31, v50
	v_lshl_add_u64 v[52:53], v[52:53], 0, s[14:15]
	v_lshl_add_u64 v[50:51], v[50:51], 2, s[2:3]
	v_lshl_add_u64 v[52:53], v[52:53], 0, v[130:131]
	v_mov_b32_e32 v50, v234
	s_nop 0
	v_mov_b32_e32 v54, v184
	v_mov_b32_e32 v55, v185
	v_pk_add_f32 v[46:47], v[46:47], v[50:51] op_sel_hi:[1,0]
	v_pk_add_f32 v[48:49], v[48:49], v[50:51] op_sel_hi:[1,0]
	v_cvt_f32_f16_e32 v56, v54
	v_cvt_f32_f16_sdwa v57, v54 dst_sel:DWORD dst_unused:UNUSED_PAD src0_sel:WORD_1
	v_cvt_f32_f16_e32 v54, v55
	v_cvt_f32_f16_sdwa v55, v55 dst_sel:DWORD dst_unused:UNUSED_PAD src0_sel:WORD_1
	v_pk_add_f32 v[42:43], v[42:43], v[50:51] op_sel_hi:[1,0]
	v_pk_mul_f32 v[46:47], v[46:47], v[56:57]
	v_pk_add_f32 v[44:45], v[44:45], v[50:51] op_sel_hi:[1,0]
	v_pk_mul_f32 v[48:49], v[48:49], v[54:55]
	v_cvt_pk_f16_f32 v46, v46, v47
	v_cvt_pk_f16_f32 v47, v48, v49
	v_lshlrev_b64 v[48:49], 11, v[210:211]
	v_lshl_add_u64 v[48:49], s[12:13], 0, v[48:49]
	v_lshl_add_u64 v[48:49], v[48:49], 0, v[130:131]
	global_store_dwordx2 v[48:49], v[46:47], off
	v_mov_b32_e32 v46, v186
	v_mov_b32_e32 v47, v187
	v_pk_add_f32 v[38:39], v[38:39], v[50:51] op_sel_hi:[1,0]
	v_pk_add_f32 v[40:41], v[40:41], v[50:51] op_sel_hi:[1,0]
	v_pk_add_f32 v[34:35], v[34:35], v[50:51] op_sel_hi:[1,0]
	v_pk_add_f32 v[36:37], v[36:37], v[50:51] op_sel_hi:[1,0]
	v_cvt_f32_f16_e32 v54, v46
	v_cvt_f32_f16_sdwa v55, v46 dst_sel:DWORD dst_unused:UNUSED_PAD src0_sel:WORD_1
	v_cvt_f32_f16_e32 v46, v47
	v_cvt_f32_f16_sdwa v47, v47 dst_sel:DWORD dst_unused:UNUSED_PAD src0_sel:WORD_1
	v_pk_mul_f32 v[42:43], v[42:43], v[54:55]
	s_nop 0
	v_cvt_pk_f16_f32 v42, v42, v43
	v_pk_mul_f32 v[44:45], v[44:45], v[46:47]
	s_nop 0
	v_cvt_pk_f16_f32 v43, v44, v45
	global_store_dwordx2 v[48:49], v[42:43], off offset:32
	v_mov_b32_e32 v42, v188
	v_mov_b32_e32 v43, v189
	v_cvt_f32_f16_e32 v44, v42
	v_cvt_f32_f16_sdwa v45, v42 dst_sel:DWORD dst_unused:UNUSED_PAD src0_sel:WORD_1
	v_cvt_f32_f16_e32 v42, v43
	v_cvt_f32_f16_sdwa v43, v43 dst_sel:DWORD dst_unused:UNUSED_PAD src0_sel:WORD_1
	v_pk_mul_f32 v[38:39], v[38:39], v[44:45]
	s_nop 0
	v_cvt_pk_f16_f32 v38, v38, v39
	v_pk_mul_f32 v[40:41], v[40:41], v[42:43]
	s_nop 0
	v_cvt_pk_f16_f32 v39, v40, v41
	global_store_dwordx2 v[48:49], v[38:39], off offset:64
	v_mov_b32_e32 v38, v190
	v_mov_b32_e32 v39, v191
	v_cvt_f32_f16_e32 v40, v38
	v_cvt_f32_f16_sdwa v41, v38 dst_sel:DWORD dst_unused:UNUSED_PAD src0_sel:WORD_1
	v_cvt_f32_f16_e32 v38, v39
	v_cvt_f32_f16_sdwa v39, v39 dst_sel:DWORD dst_unused:UNUSED_PAD src0_sel:WORD_1
	v_pk_mul_f32 v[34:35], v[34:35], v[40:41]
	s_nop 0
	v_cvt_pk_f16_f32 v34, v34, v35
	v_pk_mul_f32 v[36:37], v[36:37], v[38:39]
	s_nop 0
	v_cvt_pk_f16_f32 v35, v36, v37
	v_or_b32_e32 v36, 0x60, v219
	v_or_b32_e32 v210, v1, v36
	global_store_dwordx2 v[48:49], v[34:35], off offset:96
	v_or_b32_e32 v34, s11, v36
	v_lshlrev_b64 v[36:37], 9, v[210:211]
	v_lshl_add_u64 v[36:37], s[96:97], 0, v[36:37]
	v_ashrrev_i32_e32 v35, 31, v34
	v_lshl_add_u64 v[36:37], v[36:37], 0, s[14:15]
	v_lshl_add_u64 v[34:35], v[34:35], 2, s[2:3]
	v_lshl_add_u64 v[36:37], v[36:37], 0, v[130:131]
	v_mov_b32_e32 v34, v235
	s_nop 0
	v_mov_b32_e32 v38, v192
	v_mov_b32_e32 v39, v193
	v_pk_add_f32 v[30:31], v[30:31], v[34:35] op_sel_hi:[1,0]
	v_pk_add_f32 v[32:33], v[32:33], v[34:35] op_sel_hi:[1,0]
	v_cvt_f32_f16_e32 v40, v38
	v_cvt_f32_f16_sdwa v41, v38 dst_sel:DWORD dst_unused:UNUSED_PAD src0_sel:WORD_1
	v_cvt_f32_f16_e32 v38, v39
	v_cvt_f32_f16_sdwa v39, v39 dst_sel:DWORD dst_unused:UNUSED_PAD src0_sel:WORD_1
	v_pk_add_f32 v[26:27], v[26:27], v[34:35] op_sel_hi:[1,0]
	v_pk_mul_f32 v[30:31], v[30:31], v[40:41]
	v_pk_add_f32 v[28:29], v[28:29], v[34:35] op_sel_hi:[1,0]
	v_pk_mul_f32 v[32:33], v[32:33], v[38:39]
	v_cvt_pk_f16_f32 v30, v30, v31
	v_cvt_pk_f16_f32 v31, v32, v33
	v_lshlrev_b64 v[32:33], 11, v[210:211]
	v_lshl_add_u64 v[32:33], s[12:13], 0, v[32:33]
	v_lshl_add_u64 v[32:33], v[32:33], 0, v[130:131]
	global_store_dwordx2 v[32:33], v[30:31], off
	v_mov_b32_e32 v30, v194
	v_mov_b32_e32 v31, v195
	v_pk_add_f32 v[22:23], v[22:23], v[34:35] op_sel_hi:[1,0]
	v_pk_add_f32 v[24:25], v[24:25], v[34:35] op_sel_hi:[1,0]
	v_pk_add_f32 v[18:19], v[18:19], v[34:35] op_sel_hi:[1,0]
	v_pk_add_f32 v[20:21], v[20:21], v[34:35] op_sel_hi:[1,0]
	v_cvt_f32_f16_e32 v38, v30
	v_cvt_f32_f16_sdwa v39, v30 dst_sel:DWORD dst_unused:UNUSED_PAD src0_sel:WORD_1
	v_cvt_f32_f16_e32 v30, v31
	v_cvt_f32_f16_sdwa v31, v31 dst_sel:DWORD dst_unused:UNUSED_PAD src0_sel:WORD_1
	v_pk_mul_f32 v[26:27], v[26:27], v[38:39]
	s_nop 0
	v_cvt_pk_f16_f32 v26, v26, v27
	v_pk_mul_f32 v[28:29], v[28:29], v[30:31]
	s_nop 0
	v_cvt_pk_f16_f32 v27, v28, v29
	global_store_dwordx2 v[32:33], v[26:27], off offset:32
	v_mov_b32_e32 v26, v196
	v_mov_b32_e32 v27, v197
	v_cvt_f32_f16_e32 v28, v26
	v_cvt_f32_f16_sdwa v29, v26 dst_sel:DWORD dst_unused:UNUSED_PAD src0_sel:WORD_1
	v_cvt_f32_f16_e32 v26, v27
	v_cvt_f32_f16_sdwa v27, v27 dst_sel:DWORD dst_unused:UNUSED_PAD src0_sel:WORD_1
	v_pk_mul_f32 v[22:23], v[22:23], v[28:29]
	s_nop 0
	v_cvt_pk_f16_f32 v22, v22, v23
	v_pk_mul_f32 v[24:25], v[24:25], v[26:27]
	s_nop 0
	v_cvt_pk_f16_f32 v23, v24, v25
	global_store_dwordx2 v[32:33], v[22:23], off offset:64
	v_mov_b32_e32 v22, v198
	v_mov_b32_e32 v23, v199
	v_cvt_f32_f16_e32 v24, v22
	v_cvt_f32_f16_sdwa v25, v22 dst_sel:DWORD dst_unused:UNUSED_PAD src0_sel:WORD_1
	v_cvt_f32_f16_e32 v22, v23
	v_cvt_f32_f16_sdwa v23, v23 dst_sel:DWORD dst_unused:UNUSED_PAD src0_sel:WORD_1
	v_pk_mul_f32 v[18:19], v[18:19], v[24:25]
	s_nop 0
	v_cvt_pk_f16_f32 v18, v18, v19
	v_pk_mul_f32 v[20:21], v[20:21], v[22:23]
	s_nop 0
	v_cvt_pk_f16_f32 v19, v20, v21
	v_or_b32_e32 v20, 0x70, v219
	v_or_b32_e32 v210, v1, v20
	global_store_dwordx2 v[32:33], v[18:19], off offset:96
	v_or_b32_e32 v18, s11, v20
	v_lshlrev_b64 v[20:21], 9, v[210:211]
	v_lshl_add_u64 v[20:21], s[96:97], 0, v[20:21]
	v_ashrrev_i32_e32 v19, 31, v18
	v_lshl_add_u64 v[20:21], v[20:21], 0, s[14:15]
	v_lshl_add_u64 v[18:19], v[18:19], 2, s[2:3]
	v_lshl_add_u64 v[20:21], v[20:21], 0, v[130:131]
	v_mov_b32_e32 v18, v236
	s_nop 0
	v_mov_b32_e32 v22, v200
	v_mov_b32_e32 v23, v201
	v_pk_add_f32 v[14:15], v[14:15], v[18:19] op_sel_hi:[1,0]
	v_pk_add_f32 v[10:11], v[10:11], v[18:19] op_sel_hi:[1,0]
	v_cvt_f32_f16_e32 v24, v22
	v_cvt_f32_f16_sdwa v25, v22 dst_sel:DWORD dst_unused:UNUSED_PAD src0_sel:WORD_1
	v_pk_add_f32 v[12:13], v[12:13], v[18:19] op_sel_hi:[1,0]
	v_pk_add_f32 v[6:7], v[6:7], v[18:19] op_sel_hi:[1,0]
	v_pk_add_f32 v[8:9], v[8:9], v[18:19] op_sel_hi:[1,0]
	v_pk_mul_f32 v[14:15], v[14:15], v[24:25]
	v_pk_add_f32 v[2:3], v[2:3], v[18:19] op_sel_hi:[1,0]
	v_cvt_pk_f16_f32 v22, v14, v15
	v_pk_add_f32 v[14:15], v[16:17], v[18:19] op_sel_hi:[1,0]
	v_cvt_f32_f16_e32 v16, v23
	v_cvt_f32_f16_sdwa v17, v23 dst_sel:DWORD dst_unused:UNUSED_PAD src0_sel:WORD_1
	v_pk_add_f32 v[4:5], v[4:5], v[18:19] op_sel_hi:[1,0]
	v_pk_mul_f32 v[14:15], v[14:15], v[16:17]
	v_mov_b32_e32 v16, v202
	v_mov_b32_e32 v17, v203
	v_cvt_pk_f16_f32 v23, v14, v15
	v_lshlrev_b64 v[14:15], 11, v[210:211]
	v_lshl_add_u64 v[14:15], s[12:13], 0, v[14:15]
	v_lshl_add_u64 v[14:15], v[14:15], 0, v[130:131]
	global_store_dwordx2 v[14:15], v[22:23], off
	v_cvt_f32_f16_e32 v22, v16
	v_cvt_f32_f16_sdwa v23, v16 dst_sel:DWORD dst_unused:UNUSED_PAD src0_sel:WORD_1
	v_cvt_f32_f16_e32 v16, v17
	v_cvt_f32_f16_sdwa v17, v17 dst_sel:DWORD dst_unused:UNUSED_PAD src0_sel:WORD_1
	v_pk_mul_f32 v[10:11], v[10:11], v[22:23]
	s_nop 0
	v_cvt_pk_f16_f32 v10, v10, v11
	v_pk_mul_f32 v[12:13], v[12:13], v[16:17]
	s_nop 0
	v_cvt_pk_f16_f32 v11, v12, v13
	global_store_dwordx2 v[14:15], v[10:11], off offset:32
	v_mov_b32_e32 v10, v204
	v_mov_b32_e32 v11, v205
	v_cvt_f32_f16_e32 v12, v10
	v_cvt_f32_f16_sdwa v13, v10 dst_sel:DWORD dst_unused:UNUSED_PAD src0_sel:WORD_1
	v_cvt_f32_f16_e32 v10, v11
	v_cvt_f32_f16_sdwa v11, v11 dst_sel:DWORD dst_unused:UNUSED_PAD src0_sel:WORD_1
	v_pk_mul_f32 v[6:7], v[6:7], v[12:13]
	s_nop 0
	v_cvt_pk_f16_f32 v6, v6, v7
	v_pk_mul_f32 v[8:9], v[8:9], v[10:11]
	s_nop 0
	v_cvt_pk_f16_f32 v7, v8, v9
	global_store_dwordx2 v[14:15], v[6:7], off offset:64
	v_mov_b32_e32 v6, v206
	v_mov_b32_e32 v7, v207
	v_cvt_f32_f16_e32 v8, v6
	v_cvt_f32_f16_sdwa v9, v6 dst_sel:DWORD dst_unused:UNUSED_PAD src0_sel:WORD_1
	v_cvt_f32_f16_e32 v6, v7
	v_cvt_f32_f16_sdwa v7, v7 dst_sel:DWORD dst_unused:UNUSED_PAD src0_sel:WORD_1
	v_pk_mul_f32 v[2:3], v[2:3], v[8:9]
	s_nop 0
	v_cvt_pk_f16_f32 v2, v2, v3
	v_pk_mul_f32 v[4:5], v[4:5], v[6:7]
	s_nop 0
	v_cvt_pk_f16_f32 v3, v4, v5
	global_store_dwordx2 v[14:15], v[2:3], off offset:96
